# layer-0 branch GEMMs: the 16 context tiles of the three calls are taken by three different workgroup sets (YM tile handed over through a release flag + acquire), shortening the critical path of that p
# speedup vs baseline: 1.0502x; 1.0116x over previous
; __device__ __forceinline__ bool unit_next(const GD& g, int i, Unit& u) {
;     ...
;     if (g.sctx) {
;         nM = 64;
;         const long nb = (long)nM * nN;
;         if (L >= nb) { const int sidx = (int)(L - nb), wN = nN + g.xctx; if (sidx >= 4 * wN) return false; u.pm = 64 + sidx / wN; u.pn = sidx % wN; return true; }
;     }
.LBB0_314:
	s_and_b64 vcc, exec, s[40:41]
	s_mov_b64 s[6:7], -1
	s_cbranch_vccnz .LBB0_348
	v_mov_b64_e32 v[130:131], s[28:29]
	v_cmp_lt_i64_e64 s[6:7], s[0:1], v[130:131]
	s_and_b64 vcc, exec, s[6:7]
	s_cbranch_vccnz .LBB0_354
	s_sub_i32 s15, s0, s28
	s_cmp_lg_u32 s17, 3
	s_cbranch_scc1 .Lmy_norot
	s_lshr_b32 s4, s59, 1
	s_lshl_b32 s4, s4, 4
	s_sub_i32 s15, s15, s4
.Lmy_norot:
	v_readlane_b32 s4, v255, 14
	s_cmp_le_u32 s4, s15
	s_mov_b64 s[4:5], 0
	s_cbranch_scc1 .LBB0_318
	s_ashr_i32 s2, s15, 31
	v_readlane_b32 s4, v255, 23
	s_xor_b32 s2, s2, s4
	s_abs_i32 s4, s15
	v_readlane_b32 s5, v255, 24
	s_mul_hi_u32 s5, s4, s5
	s_mul_i32 s11, s5, s74
	s_sub_i32 s4, s4, s11
	s_add_i32 s11, s5, 1
	s_sub_i32 s34, s4, s74
	s_cmp_ge_u32 s4, s74
	s_cselect_b32 s5, s11, s5
	s_cselect_b32 s4, s34, s4
	s_add_i32 s11, s5, 1
	s_cmp_ge_u32 s4, s74
	s_cselect_b32 s4, s11, s5
	s_xor_b32 s4, s4, s2
	s_sub_i32 s2, s4, s2
	v_readlane_b32 s4, v255, 22
	s_add_i32 s11, s2, 64
	s_mul_i32 s2, s2, s4
	s_sub_i32 s2, s15, s2
	s_mov_b64 s[4:5], -1

; #define GAS __attribute__((address_space(1)))
; __device__ __forceinline__ void gemm_epilogue(LAS unsigned char* lds, const GD& gd, const f32x4 (&acc)[2][2][4][2], const Unit& u) {
;     ...
;     if (mode == M_YSET || mode == M_YADD) {
; #pragma unroll
;         for (int am = 0; am < 8 / MBG; ++am) {
;             const int ai = (am * MBG) >> 2, m0 = (am * MBG) & 3;
;             u32x4 gw[MBG][2], yw[MBG][2];
; #pragma unroll
;             for (int mm = 0; mm < MBG; ++mm)
; #pragma unroll
;                 for (int bj = 0; bj < 2; ++bj) {
;                     const int ro = ai * HALF + (m0 + mm) * 16;
;                     gw[mm][bj] = *(GAS const u32x4*)(auxu + goff + ro * apitch + bj * HALF);
;                     if (mode == M_YADD) yw[mm][bj] = *(GAS const u32x4*)(outu + ooff + ro * ldc + bj * HALF);
;                 }
;             asm volatile("" ::: "memory");
.LBB0_555:
	s_and_b64 vcc, exec, s[6:7]
	s_cbranch_vccz .LBB0_621
	s_cmp_lt_i32 s33, 64
	s_cbranch_scc1 .Lmy_cnop
	s_cmp_lt_u32 s59, 3
	s_cbranch_scc1 .Lmy_cnop
	v_mov_b32_e32 v132, 0x240a8
	ds_read_b64 v[132:133], v132
	s_lshr_b32 s50, s59, 1
	s_sub_u32 s50, s50, 1
	s_lshl_b32 s50, s50, 4
	s_sub_u32 s51, s33, 64
	s_lshl_b32 s51, s51, 2
	s_add_u32 s50, s50, s51
	s_add_u32 s50, s50, s80
	s_lshl_b32 s50, s50, 2
	s_add_u32 s50, s50, 0x100040
	s_waitcnt lgkmcnt(0)
	v_readfirstlane_b32 s48, v132
	v_readfirstlane_b32 s49, v133
	s_nop 3
	s_add_u32 s48, s48, s50
	s_addc_u32 s49, s49, 0
	s_mov_b32 s51, 0
.Lmy_spin:
	global_load_dword v132, v97, s[48:49] sc1
	s_waitcnt vmcnt(0)
	v_readfirstlane_b32 s50, v132
	s_cmp_lg_u32 s50, 0
	s_cbranch_scc1 .Lmy_got
	s_sleep 4
	s_add_u32 s51, s51, 1
	s_cmp_lt_u32 s51, 0x20000
	s_cbranch_scc1 .Lmy_spin
.Lmy_got:
	buffer_inv sc1
	s_waitcnt vmcnt(0)
.Lmy_cnop:
	s_cmp_eq_u32 s78, 4
	s_cselect_b64 s[4:5], -1, 0
	s_and_b64 s[6:7], s[94:95], exec
	s_movk_i32 s2, 0xc00
	s_cselect_b32 s6, s2, 0x400
	v_mul_lo_u32 v132, v174, s6
	v_or_b32_e32 v96, v132, v96
	s_and_b64 s[46:47], s[94:95], exec
	s_cbranch_scc1 .Lmy_nogf2
	v_mov_b32_e32 v132, 0x240a8
	ds_read_b64 v[132:133], v132
	s_and_b32 s46, s15, 1
	s_lshl_b32 s46, s46, 12
	s_lshr_b32 s47, s15, 1
	s_lshl_b32 s48, s98, 1
	s_add_u32 s47, s47, s48
	s_lshl_b32 s47, s47, 14
	s_add_u32 s46, s46, s47
	v_lshlrev_b32_e32 v96, 8, v251
	v_lshl_add_u32 v96, v252, 3, v96
	v_add_u32_e32 v96, s46, v96
	s_movk_i32 s6, 64
	s_lshl_b32 s46, s33, 19
	s_lshl_b32 s47, s80, 17
	s_add_u32 s46, s46, s47
	s_add_u32 s46, s46, 0x6300000
	s_waitcnt lgkmcnt(0)
	v_readfirstlane_b32 s96, v132
	v_readfirstlane_b32 s97, v133
	s_nop 3
	s_add_u32 s96, s96, s46
	s_addc_u32 s97, s97, 0

; __device__ __forceinline__ unsigned pk2(float lo, float hi) { unsigned r; asm volatile("v_cvt_pk_bf16_f32 %0, %1, %2" : "=v"(r) : "v"(lo), "v"(hi)); return r; }
; #define GAS __attribute__((address_space(1)))
; __device__ __forceinline__ void gemm_epilogue(LAS unsigned char* lds, const GD& gd, const f32x4 (&acc)[2][2][4][2], const Unit& u) {
;     ...
;                     u32x4 w; w.x = pk2(v0[0], v0[1]); w.y = pk2(v0[2], v0[3]); w.z = pk2(v1[0], v1[1]); w.w = pk2(v1[2], v1[3]);
;                     *(GAS u32x4*)(outu + ooff + (ai * HALF + m * 16) * ldc + bj * HALF) = w;
;                 }
;             }
.LBB0_620:
	v_cvt_pk_bf16_f32 v132, v136, v137
	v_cvt_pk_bf16_f32 v133, v138, v139
	v_cvt_pk_bf16_f32 v134, v140, v141
	s_nop 0
	v_cvt_pk_bf16_f32 v135, v142, v143
	global_store_dwordx4 v[164:165], v[132:135], off offset:256
	s_cmp_lt_i32 s33, 64
	s_cbranch_scc1 .LBB0_621
	s_cmp_gt_u32 s59, 3
	s_cbranch_scc1 .LBB0_621
	s_waitcnt vmcnt(0)
	s_barrier
	v_cmp_eq_u32_e32 vcc, 0, v210
	s_and_saveexec_b64 s[46:47], vcc
	s_cbranch_execz .Lmy_pdone
	buffer_wbl2 sc1
	s_waitcnt vmcnt(0)
	v_mov_b32_e32 v132, 0x240a8
	ds_read_b64 v[132:133], v132
	s_lshr_b32 s50, s59, 1
	s_lshl_b32 s50, s50, 4
	s_sub_u32 s51, s33, 64
	s_lshl_b32 s51, s51, 2
	s_add_u32 s50, s50, s51
	s_add_u32 s50, s50, s80
	s_lshl_b32 s50, s50, 2
	s_add_u32 s50, s50, 0x100040
	s_waitcnt lgkmcnt(0)
	v_readfirstlane_b32 s48, v132
	v_readfirstlane_b32 s49, v133
	s_nop 3
	s_add_u32 s48, s48, s50
	s_addc_u32 s49, s49, 0
	v_mov_b32_e32 v132, 1
	s_nop 0
	global_atomic_add v97, v132, s[48:49]
	s_waitcnt vmcnt(0)
.Lmy_pdone:
	s_or_b64 exec, exec, s[46:47]
.LBB0_621:
.LBB0_622:
	s_and_b64 vcc, exec, s[42:43]
	s_cbranch_vccnz .LBB0_309
